# combo2 + vtrans: the 16 row loads of an item issued together (counted waits) instead of one round trip each
# baseline (speedup 1.0000x reference)
.LBB0_490:
	s_bfe_u32 s3, s4, 0x1000a
	s_lshl_b32 s20, s3, 14
	s_and_b32 s26, s22, 0x3fc0
	s_or_b32 s20, s20, s26
	s_bfe_u32 s2, s4, 0x20008
	s_mulk_i32 s20, 0x3400
	s_add_u32 s27, s78, s20
	s_addc_u32 s30, s79, 0
	s_cmpk_lt_u32 s4, 0x800
	s_movk_i32 s20, 0xe00
	s_cselect_b32 s20, s20, 0x1200
	s_mov_b32 s21, 0x47600000
	s_cselect_b32 s31, s36, 0x1000
	s_cselect_b32 s34, s21, 0x48600000
	s_add_u32 s20, s27, s20
	s_addc_u32 s21, s30, 0
	s_lshl_b32 s35, s2, 7
	s_add_u32 s20, s20, s35
	s_addc_u32 s21, s21, 0
	v_lshl_add_u64 v[50:51], s[20:21], 0, v[2:3]
	v_lshlrev_b32_e32 v40, 1, v0
	v_mov_b32_e32 v41, v16
	v_lshl_add_u64 v[50:51], v[50:51], 0, v[40:41]
	global_load_dwordx4 v[88:91], v[50:51], off
	s_add_u32 s27, s27, s31
	s_addc_u32 s30, s30, 0
	s_add_u32 s31, s6, s34
	s_addc_u32 s34, s7, 0
	s_lshl_b32 s3, s3, 16
	s_lshl_b32 s2, s2, 14
	s_or_b32 s2, s3, s2
	s_or_b32 s2, s2, s26
	s_lshl_b32 s2, s2, 6
	s_add_u32 s2, s31, s2
	s_addc_u32 s3, s34, 0
	v_lshl_add_u64 v[50:51], s[20:21], 0, v[4:5]
	v_lshl_add_u64 v[50:51], v[50:51], 0, v[40:41]
	global_load_dwordx4 v[92:95], v[50:51], off
	v_lshl_add_u64 v[50:51], s[20:21], 0, v[6:7]
	v_lshl_add_u64 v[50:51], v[50:51], 0, v[40:41]
	global_load_dwordx4 v[96:99], v[50:51], off
	v_lshl_add_u64 v[50:51], s[20:21], 0, v[8:9]
	v_lshl_add_u64 v[50:51], v[50:51], 0, v[40:41]
	global_load_dwordx4 v[100:103], v[50:51], off
	v_lshl_add_u64 v[50:51], s[20:21], 0, v[10:11]
	v_lshl_add_u64 v[50:51], v[50:51], 0, v[40:41]
	global_load_dwordx4 v[104:107], v[50:51], off
	v_lshl_add_u64 v[50:51], s[20:21], 0, v[12:13]
	v_lshl_add_u64 v[50:51], v[50:51], 0, v[40:41]
	global_load_dwordx4 v[108:111], v[50:51], off
	v_lshl_add_u64 v[50:51], s[20:21], 0, v[14:15]
	v_lshl_add_u64 v[50:51], v[50:51], 0, v[40:41]
	global_load_dwordx4 v[112:115], v[50:51], off
	v_lshl_add_u64 v[50:51], s[20:21], 0, v[18:19]
	v_lshl_add_u64 v[50:51], v[50:51], 0, v[40:41]
	global_load_dwordx4 v[116:119], v[50:51], off
	s_add_u32 s20, s27, s35
	s_addc_u32 s21, s30, 0
	v_lshl_add_u64 v[50:51], s[20:21], 0, v[2:3]
	v_lshl_add_u64 v[50:51], v[50:51], 0, v[40:41]
	global_load_dwordx4 v[120:123], v[50:51], off
	v_lshl_add_u64 v[50:51], s[20:21], 0, v[4:5]
	v_lshl_add_u64 v[50:51], v[50:51], 0, v[40:41]
	global_load_dwordx4 v[124:127], v[50:51], off
	v_lshl_add_u64 v[50:51], s[20:21], 0, v[6:7]
	v_lshl_add_u64 v[50:51], v[50:51], 0, v[40:41]
	global_load_dwordx4 v[128:131], v[50:51], off
	v_lshl_add_u64 v[50:51], s[20:21], 0, v[8:9]
	v_lshl_add_u64 v[50:51], v[50:51], 0, v[40:41]
	global_load_dwordx4 v[136:139], v[50:51], off
	v_lshl_add_u64 v[50:51], s[20:21], 0, v[10:11]
	v_lshl_add_u64 v[50:51], v[50:51], 0, v[40:41]
	global_load_dwordx4 v[140:143], v[50:51], off
	v_lshl_add_u64 v[50:51], s[20:21], 0, v[12:13]
	v_lshl_add_u64 v[50:51], v[50:51], 0, v[40:41]
	global_load_dwordx4 v[144:147], v[50:51], off
	v_lshl_add_u64 v[50:51], s[20:21], 0, v[14:15]
	v_lshl_add_u64 v[50:51], v[50:51], 0, v[40:41]
	global_load_dwordx4 v[148:151], v[50:51], off
	v_lshl_add_u64 v[50:51], s[20:21], 0, v[18:19]
	v_lshl_add_u64 v[40:41], v[50:51], 0, v[40:41]
	global_load_dwordx4 v[60:63], v[40:41], off
	v_mov_b32_e32 v40, v16
	s_waitcnt vmcnt(15)
	ds_write2_b64 v17, v[88:89], v[90:91] offset1:1
	s_waitcnt vmcnt(14)
	ds_write2_b64 v42, v[92:93], v[94:95] offset1:1
	s_waitcnt vmcnt(13)
	ds_write2_b64 v43, v[96:97], v[98:99] offset1:1
	s_waitcnt vmcnt(12)
	ds_write2_b64 v44, v[100:101], v[102:103] offset1:1
	s_waitcnt vmcnt(11)
	ds_write2_b64 v45, v[104:105], v[106:107] offset1:1
	s_waitcnt vmcnt(10)
	ds_write2_b64 v46, v[108:109], v[110:111] offset1:1
	s_waitcnt vmcnt(9)
	ds_write2_b64 v47, v[112:113], v[114:115] offset1:1
	s_waitcnt vmcnt(8)
	ds_write2_b64 v48, v[116:117], v[118:119] offset1:1
	s_waitcnt vmcnt(0)
	v_lshlrev_b32_e32 v54, 16, v120
	v_and_b32_e32 v55, 0xffff0000, v120
	v_mov_b32_e32 v50, v16
	v_cvt_pk_fp8_f32 v50, v54, v55
	v_lshlrev_b32_e32 v56, 16, v121
	v_and_b32_e32 v51, 0xffff0000, v121
	v_lshlrev_b32_e32 v54, 16, v122
	v_cvt_pk_fp8_f32 v50, v56, v51 op_sel:[0,0,1]
	v_and_b32_e32 v52, 0xffff0000, v122
	v_mov_b32_e32 v51, v16
	v_cvt_pk_fp8_f32 v51, v54, v52
	v_lshlrev_b32_e32 v55, 16, v123
	v_and_b32_e32 v53, 0xffff0000, v123
	v_cvt_pk_fp8_f32 v51, v55, v53 op_sel:[0,0,1]
	v_lshl_add_u64 v[52:53], s[2:3], 0, v[20:21]
	v_lshl_add_u64 v[52:53], v[52:53], 0, v[22:23]
	v_lshl_add_u64 v[52:53], v[52:53], 0, v[24:25]
	flat_store_dwordx2 v[52:53], v[50:51]
	v_lshlrev_b32_e32 v54, 16, v124
	v_and_b32_e32 v55, 0xffff0000, v124
	v_mov_b32_e32 v50, v16
	v_cvt_pk_fp8_f32 v50, v54, v55
	v_lshlrev_b32_e32 v56, 16, v125
	v_and_b32_e32 v51, 0xffff0000, v125
	v_lshlrev_b32_e32 v54, 16, v126
	v_cvt_pk_fp8_f32 v50, v56, v51 op_sel:[0,0,1]
	v_and_b32_e32 v52, 0xffff0000, v126
	v_mov_b32_e32 v51, v16
	v_cvt_pk_fp8_f32 v51, v54, v52
	v_lshlrev_b32_e32 v55, 16, v127
	v_and_b32_e32 v53, 0xffff0000, v127
	v_cvt_pk_fp8_f32 v51, v55, v53 op_sel:[0,0,1]
	v_lshl_add_u64 v[52:53], s[2:3], 0, v[26:27]
	v_lshl_add_u64 v[52:53], v[52:53], 0, v[22:23]
	v_lshl_add_u64 v[52:53], v[52:53], 0, v[24:25]
	flat_store_dwordx2 v[52:53], v[50:51]
	v_lshlrev_b32_e32 v54, 16, v128
	v_and_b32_e32 v55, 0xffff0000, v128
	v_mov_b32_e32 v50, v16
	v_cvt_pk_fp8_f32 v50, v54, v55
	v_lshlrev_b32_e32 v56, 16, v129
	v_and_b32_e32 v51, 0xffff0000, v129
	v_lshlrev_b32_e32 v54, 16, v130
	v_cvt_pk_fp8_f32 v50, v56, v51 op_sel:[0,0,1]
	v_and_b32_e32 v52, 0xffff0000, v130
	v_mov_b32_e32 v51, v16
	v_cvt_pk_fp8_f32 v51, v54, v52
	v_lshlrev_b32_e32 v55, 16, v131
	v_and_b32_e32 v53, 0xffff0000, v131
	v_cvt_pk_fp8_f32 v51, v55, v53 op_sel:[0,0,1]
	v_lshl_add_u64 v[52:53], s[2:3], 0, v[28:29]
	v_lshl_add_u64 v[52:53], v[52:53], 0, v[22:23]
	v_lshl_add_u64 v[52:53], v[52:53], 0, v[24:25]
	flat_store_dwordx2 v[52:53], v[50:51]
	v_lshlrev_b32_e32 v54, 16, v136
	v_and_b32_e32 v55, 0xffff0000, v136
	v_mov_b32_e32 v50, v16
	v_cvt_pk_fp8_f32 v50, v54, v55
	v_lshlrev_b32_e32 v56, 16, v137
	v_and_b32_e32 v51, 0xffff0000, v137
	v_lshlrev_b32_e32 v54, 16, v138
	v_cvt_pk_fp8_f32 v50, v56, v51 op_sel:[0,0,1]
	v_and_b32_e32 v52, 0xffff0000, v138
	v_mov_b32_e32 v51, v16
	v_cvt_pk_fp8_f32 v51, v54, v52
	v_lshlrev_b32_e32 v55, 16, v139
	v_and_b32_e32 v53, 0xffff0000, v139
	v_cvt_pk_fp8_f32 v51, v55, v53 op_sel:[0,0,1]
	v_lshl_add_u64 v[52:53], s[2:3], 0, v[30:31]
	v_lshl_add_u64 v[52:53], v[52:53], 0, v[22:23]
	v_lshl_add_u64 v[52:53], v[52:53], 0, v[24:25]
	flat_store_dwordx2 v[52:53], v[50:51]
	v_lshlrev_b32_e32 v54, 16, v140
	v_and_b32_e32 v55, 0xffff0000, v140
	v_mov_b32_e32 v50, v16
	v_cvt_pk_fp8_f32 v50, v54, v55
	v_lshlrev_b32_e32 v56, 16, v141
	v_and_b32_e32 v51, 0xffff0000, v141
	v_lshlrev_b32_e32 v54, 16, v142
	v_cvt_pk_fp8_f32 v50, v56, v51 op_sel:[0,0,1]
	v_and_b32_e32 v52, 0xffff0000, v142
	v_mov_b32_e32 v51, v16
	v_cvt_pk_fp8_f32 v51, v54, v52
	v_lshlrev_b32_e32 v55, 16, v143
	v_and_b32_e32 v53, 0xffff0000, v143
	v_cvt_pk_fp8_f32 v51, v55, v53 op_sel:[0,0,1]
	v_lshl_add_u64 v[52:53], s[2:3], 0, v[32:33]
	v_lshl_add_u64 v[52:53], v[52:53], 0, v[22:23]
	v_lshl_add_u64 v[52:53], v[52:53], 0, v[24:25]
	flat_store_dwordx2 v[52:53], v[50:51]
	v_lshlrev_b32_e32 v54, 16, v144
	v_and_b32_e32 v55, 0xffff0000, v144
	v_mov_b32_e32 v50, v16
	v_cvt_pk_fp8_f32 v50, v54, v55
	v_lshlrev_b32_e32 v56, 16, v145
	v_and_b32_e32 v51, 0xffff0000, v145
	v_lshlrev_b32_e32 v54, 16, v146
	v_cvt_pk_fp8_f32 v50, v56, v51 op_sel:[0,0,1]
	v_and_b32_e32 v52, 0xffff0000, v146
	v_mov_b32_e32 v51, v16
	v_cvt_pk_fp8_f32 v51, v54, v52
	v_lshlrev_b32_e32 v55, 16, v147
	v_and_b32_e32 v53, 0xffff0000, v147
	v_cvt_pk_fp8_f32 v51, v55, v53 op_sel:[0,0,1]
	v_lshl_add_u64 v[52:53], s[2:3], 0, v[34:35]
	v_lshl_add_u64 v[52:53], v[52:53], 0, v[22:23]
	v_lshl_add_u64 v[52:53], v[52:53], 0, v[24:25]
	flat_store_dwordx2 v[52:53], v[50:51]
	v_lshlrev_b32_e32 v54, 16, v148
	v_and_b32_e32 v55, 0xffff0000, v148
	v_mov_b32_e32 v50, v16
	v_cvt_pk_fp8_f32 v50, v54, v55
	v_lshlrev_b32_e32 v56, 16, v149
	v_and_b32_e32 v51, 0xffff0000, v149
	v_lshlrev_b32_e32 v54, 16, v150
	v_cvt_pk_fp8_f32 v50, v56, v51 op_sel:[0,0,1]
	v_and_b32_e32 v52, 0xffff0000, v150
	v_mov_b32_e32 v51, v16
	v_cvt_pk_fp8_f32 v51, v54, v52
	v_lshlrev_b32_e32 v55, 16, v151
	v_and_b32_e32 v53, 0xffff0000, v151
	v_cvt_pk_fp8_f32 v51, v55, v53 op_sel:[0,0,1]
	v_lshl_add_u64 v[52:53], s[2:3], 0, v[36:37]
	v_lshl_add_u64 v[52:53], v[52:53], 0, v[22:23]
	v_lshl_add_u64 v[52:53], v[52:53], 0, v[24:25]
	flat_store_dwordx2 v[52:53], v[50:51]
	v_lshlrev_b32_e32 v41, 16, v60
	v_and_b32_e32 v50, 0xffff0000, v60
	v_cvt_pk_fp8_f32 v40, v41, v50
	v_lshlrev_b32_e32 v54, 16, v61
	v_and_b32_e32 v51, 0xffff0000, v61
	v_lshlrev_b32_e32 v50, 16, v62
	v_cvt_pk_fp8_f32 v40, v54, v51 op_sel:[0,0,1]
	v_and_b32_e32 v51, 0xffff0000, v62
	v_mov_b32_e32 v41, v16
	v_cvt_pk_fp8_f32 v41, v50, v51
	v_lshlrev_b32_e32 v52, 16, v63
	v_and_b32_e32 v53, 0xffff0000, v63
	v_lshl_add_u64 v[50:51], s[2:3], 0, v[38:39]
	v_cvt_pk_fp8_f32 v41, v52, v53 op_sel:[0,0,1]
	v_lshl_add_u64 v[50:51], v[50:51], 0, v[22:23]
	v_lshl_add_u64 v[50:51], v[50:51], 0, v[24:25]
	s_add_u32 s2, s2, 0x800000
	flat_store_dwordx2 v[50:51], v[40:41]
	s_waitcnt lgkmcnt(0)
	ds_read_u16 v40, v49
	s_addc_u32 s3, s3, 0
	s_add_i32 s4, s4, s5
	s_add_i32 s22, s22, s23
	s_cmpk_lt_i32 s4, 0x1000
	s_waitcnt lgkmcnt(0)
	v_lshlrev_b32_e32 v41, 16, v40
	ds_read_u16 v40, v49 offset:136
	s_waitcnt lgkmcnt(0)
	v_lshlrev_b32_e32 v50, 16, v40
	ds_read_u16 v40, v49 offset:272
	s_waitcnt lgkmcnt(0)
	v_lshlrev_b32_e32 v51, 16, v40
	ds_read_u16 v40, v49 offset:408
	s_waitcnt lgkmcnt(0)
	v_lshlrev_b32_e32 v52, 16, v40
	ds_read_u16 v40, v49 offset:2176
	s_waitcnt lgkmcnt(0)
	v_lshlrev_b32_e32 v53, 16, v40
	ds_read_u16 v40, v49 offset:2312
	s_waitcnt lgkmcnt(0)
	v_lshlrev_b32_e32 v54, 16, v40
	ds_read_u16 v40, v49 offset:2448
	s_waitcnt lgkmcnt(0)
	v_lshlrev_b32_e32 v55, 16, v40
	ds_read_u16 v40, v49 offset:2584
	s_waitcnt lgkmcnt(0)
	v_lshlrev_b32_e32 v56, 16, v40
	v_mov_b32_e32 v40, v16
	v_cvt_pk_fp8_f32 v40, v41, v50
	v_mov_b32_e32 v41, v16
	v_cvt_pk_fp8_f32 v41, v53, v54
	v_cvt_pk_fp8_f32 v40, v51, v52 op_sel:[0,0,1]
	v_lshl_add_u64 v[50:51], s[2:3], 0, v[20:21]
	v_cvt_pk_fp8_f32 v41, v55, v56 op_sel:[0,0,1]
	v_lshl_add_u64 v[50:51], v[50:51], 0, v[0:1]
	flat_store_dwordx2 v[50:51], v[40:41]
	ds_read_u16 v40, v49 offset:16
	s_waitcnt lgkmcnt(0)
	v_lshlrev_b32_e32 v41, 16, v40
	ds_read_u16 v40, v49 offset:152
	s_waitcnt lgkmcnt(0)
	v_lshlrev_b32_e32 v50, 16, v40
	ds_read_u16 v40, v49 offset:288
	s_waitcnt lgkmcnt(0)
	v_lshlrev_b32_e32 v51, 16, v40
	ds_read_u16 v40, v49 offset:424
	s_waitcnt lgkmcnt(0)
	v_lshlrev_b32_e32 v52, 16, v40
	ds_read_u16 v40, v49 offset:2192
	s_waitcnt lgkmcnt(0)
	v_lshlrev_b32_e32 v53, 16, v40
	ds_read_u16 v40, v49 offset:2328
	s_waitcnt lgkmcnt(0)
	v_lshlrev_b32_e32 v54, 16, v40
	ds_read_u16 v40, v49 offset:2464
	s_waitcnt lgkmcnt(0)
	v_lshlrev_b32_e32 v55, 16, v40
	ds_read_u16 v40, v49 offset:2600
	s_waitcnt lgkmcnt(0)
	v_lshlrev_b32_e32 v56, 16, v40
	v_mov_b32_e32 v40, v16
	v_cvt_pk_fp8_f32 v40, v41, v50
	v_mov_b32_e32 v41, v16
	v_cvt_pk_fp8_f32 v41, v53, v54
	v_cvt_pk_fp8_f32 v40, v51, v52 op_sel:[0,0,1]
	v_lshl_add_u64 v[50:51], s[2:3], 0, v[26:27]
	v_cvt_pk_fp8_f32 v41, v55, v56 op_sel:[0,0,1]
	v_lshl_add_u64 v[50:51], v[50:51], 0, v[0:1]
	flat_store_dwordx2 v[50:51], v[40:41]
	ds_read_u16 v40, v49 offset:32
	s_waitcnt lgkmcnt(0)
	v_lshlrev_b32_e32 v41, 16, v40
	ds_read_u16 v40, v49 offset:168
	s_waitcnt lgkmcnt(0)
	v_lshlrev_b32_e32 v50, 16, v40
	ds_read_u16 v40, v49 offset:304
	s_waitcnt lgkmcnt(0)
	v_lshlrev_b32_e32 v51, 16, v40
	ds_read_u16 v40, v49 offset:440
	s_waitcnt lgkmcnt(0)
	v_lshlrev_b32_e32 v52, 16, v40
	ds_read_u16 v40, v49 offset:2208
	s_waitcnt lgkmcnt(0)
	v_lshlrev_b32_e32 v53, 16, v40
	ds_read_u16 v40, v49 offset:2344
	s_waitcnt lgkmcnt(0)
	v_lshlrev_b32_e32 v54, 16, v40
	ds_read_u16 v40, v49 offset:2480
	s_waitcnt lgkmcnt(0)
	v_lshlrev_b32_e32 v55, 16, v40
	ds_read_u16 v40, v49 offset:2616
	s_waitcnt lgkmcnt(0)
	v_lshlrev_b32_e32 v56, 16, v40
	v_mov_b32_e32 v40, v16
	v_cvt_pk_fp8_f32 v40, v41, v50
	v_mov_b32_e32 v41, v16
	v_cvt_pk_fp8_f32 v41, v53, v54
	v_cvt_pk_fp8_f32 v40, v51, v52 op_sel:[0,0,1]
	v_lshl_add_u64 v[50:51], s[2:3], 0, v[28:29]
	v_cvt_pk_fp8_f32 v41, v55, v56 op_sel:[0,0,1]
	v_lshl_add_u64 v[50:51], v[50:51], 0, v[0:1]
	flat_store_dwordx2 v[50:51], v[40:41]
	ds_read_u16 v40, v49 offset:48
	s_waitcnt lgkmcnt(0)
	v_lshlrev_b32_e32 v41, 16, v40
	ds_read_u16 v40, v49 offset:184
	s_waitcnt lgkmcnt(0)
	v_lshlrev_b32_e32 v50, 16, v40
	ds_read_u16 v40, v49 offset:320
	s_waitcnt lgkmcnt(0)
	v_lshlrev_b32_e32 v51, 16, v40
	ds_read_u16 v40, v49 offset:456
	s_waitcnt lgkmcnt(0)
	v_lshlrev_b32_e32 v52, 16, v40
	ds_read_u16 v40, v49 offset:2224
	s_waitcnt lgkmcnt(0)
	v_lshlrev_b32_e32 v53, 16, v40
	ds_read_u16 v40, v49 offset:2360
	s_waitcnt lgkmcnt(0)
	v_lshlrev_b32_e32 v54, 16, v40
	ds_read_u16 v40, v49 offset:2496
	s_waitcnt lgkmcnt(0)
	v_lshlrev_b32_e32 v55, 16, v40
	ds_read_u16 v40, v49 offset:2632
	s_waitcnt lgkmcnt(0)
	v_lshlrev_b32_e32 v56, 16, v40
	v_mov_b32_e32 v40, v16
	v_cvt_pk_fp8_f32 v40, v41, v50
	v_mov_b32_e32 v41, v16
	v_cvt_pk_fp8_f32 v41, v53, v54
	v_cvt_pk_fp8_f32 v40, v51, v52 op_sel:[0,0,1]
	v_lshl_add_u64 v[50:51], s[2:3], 0, v[30:31]
	v_cvt_pk_fp8_f32 v41, v55, v56 op_sel:[0,0,1]
	v_lshl_add_u64 v[50:51], v[50:51], 0, v[0:1]
	flat_store_dwordx2 v[50:51], v[40:41]
	ds_read_u16 v40, v49 offset:64
	s_waitcnt lgkmcnt(0)
	v_lshlrev_b32_e32 v41, 16, v40
	ds_read_u16 v40, v49 offset:200
	s_waitcnt lgkmcnt(0)
	v_lshlrev_b32_e32 v50, 16, v40
	ds_read_u16 v40, v49 offset:336
	s_waitcnt lgkmcnt(0)
	v_lshlrev_b32_e32 v51, 16, v40
	ds_read_u16 v40, v49 offset:472
	s_waitcnt lgkmcnt(0)
	v_lshlrev_b32_e32 v52, 16, v40
	ds_read_u16 v40, v49 offset:2240
	s_waitcnt lgkmcnt(0)
	v_lshlrev_b32_e32 v53, 16, v40
	ds_read_u16 v40, v49 offset:2376
	s_waitcnt lgkmcnt(0)
	v_lshlrev_b32_e32 v54, 16, v40
	ds_read_u16 v40, v49 offset:2512
	s_waitcnt lgkmcnt(0)
	v_lshlrev_b32_e32 v55, 16, v40
	ds_read_u16 v40, v49 offset:2648
	s_waitcnt lgkmcnt(0)
	v_lshlrev_b32_e32 v56, 16, v40
	v_mov_b32_e32 v40, v16
	v_cvt_pk_fp8_f32 v40, v41, v50
	v_mov_b32_e32 v41, v16
	v_cvt_pk_fp8_f32 v41, v53, v54
	v_cvt_pk_fp8_f32 v40, v51, v52 op_sel:[0,0,1]
	v_lshl_add_u64 v[50:51], s[2:3], 0, v[32:33]
	v_cvt_pk_fp8_f32 v41, v55, v56 op_sel:[0,0,1]
	v_lshl_add_u64 v[50:51], v[50:51], 0, v[0:1]
	flat_store_dwordx2 v[50:51], v[40:41]
	ds_read_u16 v40, v49 offset:80
	s_waitcnt lgkmcnt(0)
	v_lshlrev_b32_e32 v41, 16, v40
	ds_read_u16 v40, v49 offset:216
	s_waitcnt lgkmcnt(0)
	v_lshlrev_b32_e32 v50, 16, v40
	ds_read_u16 v40, v49 offset:352
	s_waitcnt lgkmcnt(0)
	v_lshlrev_b32_e32 v51, 16, v40
	ds_read_u16 v40, v49 offset:488
	s_waitcnt lgkmcnt(0)
	v_lshlrev_b32_e32 v52, 16, v40
	ds_read_u16 v40, v49 offset:2256
	s_waitcnt lgkmcnt(0)
	v_lshlrev_b32_e32 v53, 16, v40
	ds_read_u16 v40, v49 offset:2392
	s_waitcnt lgkmcnt(0)
	v_lshlrev_b32_e32 v54, 16, v40
	ds_read_u16 v40, v49 offset:2528
	s_waitcnt lgkmcnt(0)
	v_lshlrev_b32_e32 v55, 16, v40
	ds_read_u16 v40, v49 offset:2664
	s_waitcnt lgkmcnt(0)
	v_lshlrev_b32_e32 v56, 16, v40
	v_mov_b32_e32 v40, v16
	v_cvt_pk_fp8_f32 v40, v41, v50
	v_mov_b32_e32 v41, v16
	v_cvt_pk_fp8_f32 v41, v53, v54
	v_cvt_pk_fp8_f32 v40, v51, v52 op_sel:[0,0,1]
	v_lshl_add_u64 v[50:51], s[2:3], 0, v[34:35]
	v_cvt_pk_fp8_f32 v41, v55, v56 op_sel:[0,0,1]
	v_lshl_add_u64 v[50:51], v[50:51], 0, v[0:1]
	flat_store_dwordx2 v[50:51], v[40:41]
	ds_read_u16 v40, v49 offset:96
	s_waitcnt lgkmcnt(0)
	v_lshlrev_b32_e32 v41, 16, v40
	ds_read_u16 v40, v49 offset:232
	s_waitcnt lgkmcnt(0)
	v_lshlrev_b32_e32 v50, 16, v40
	ds_read_u16 v40, v49 offset:368
	s_waitcnt lgkmcnt(0)
	v_lshlrev_b32_e32 v51, 16, v40
	ds_read_u16 v40, v49 offset:504
	s_waitcnt lgkmcnt(0)
	v_lshlrev_b32_e32 v52, 16, v40
	ds_read_u16 v40, v49 offset:2272
	s_waitcnt lgkmcnt(0)
	v_lshlrev_b32_e32 v53, 16, v40
	ds_read_u16 v40, v49 offset:2408
	s_waitcnt lgkmcnt(0)
	v_lshlrev_b32_e32 v54, 16, v40
	ds_read_u16 v40, v49 offset:2544
	s_waitcnt lgkmcnt(0)
	v_lshlrev_b32_e32 v55, 16, v40
	ds_read_u16 v40, v49 offset:2680
	s_waitcnt lgkmcnt(0)
	v_lshlrev_b32_e32 v56, 16, v40
	v_mov_b32_e32 v40, v16
	v_cvt_pk_fp8_f32 v40, v41, v50
	v_mov_b32_e32 v41, v16
	v_cvt_pk_fp8_f32 v41, v53, v54
	v_cvt_pk_fp8_f32 v40, v51, v52 op_sel:[0,0,1]
	v_lshl_add_u64 v[50:51], s[2:3], 0, v[36:37]
	v_cvt_pk_fp8_f32 v41, v55, v56 op_sel:[0,0,1]
	v_lshl_add_u64 v[50:51], v[50:51], 0, v[0:1]
	flat_store_dwordx2 v[50:51], v[40:41]
	ds_read_u16 v40, v49 offset:112
	s_waitcnt lgkmcnt(0)
	v_lshlrev_b32_e32 v41, 16, v40
	ds_read_u16 v40, v49 offset:248
	s_waitcnt lgkmcnt(0)
	v_lshlrev_b32_e32 v54, 16, v40
	ds_read_u16 v40, v49 offset:384
	s_waitcnt lgkmcnt(0)
	v_lshlrev_b32_e32 v55, 16, v40
	ds_read_u16 v40, v49 offset:520
	s_waitcnt lgkmcnt(0)
	v_lshlrev_b32_e32 v56, 16, v40
	ds_read_u16 v40, v49 offset:2288
	s_waitcnt lgkmcnt(0)
	v_lshlrev_b32_e32 v52, 16, v40
	ds_read_u16 v40, v49 offset:2424
	s_waitcnt lgkmcnt(0)
	v_lshlrev_b32_e32 v53, 16, v40
	ds_read_u16 v40, v49 offset:2560
	s_waitcnt lgkmcnt(0)
	v_lshlrev_b32_e32 v50, 16, v40
	ds_read_u16 v40, v49 offset:2696
	s_waitcnt lgkmcnt(0)
	v_lshlrev_b32_e32 v51, 16, v40
	v_mov_b32_e32 v40, v16
	v_cvt_pk_fp8_f32 v40, v41, v54
	v_mov_b32_e32 v41, v16
	v_cvt_pk_fp8_f32 v41, v52, v53
	v_cvt_pk_fp8_f32 v40, v55, v56 op_sel:[0,0,1]
	v_cvt_pk_fp8_f32 v41, v50, v51 op_sel:[0,0,1]
	v_lshl_add_u64 v[50:51], s[2:3], 0, v[38:39]
	v_lshl_add_u64 v[50:51], v[50:51], 0, v[0:1]
	flat_store_dwordx2 v[50:51], v[40:41]
	s_waitcnt lgkmcnt(0)
	s_cbranch_scc1 .LBB0_490
